# more early exps in QK MFMA gaps (24 of 64 MLA, 12 of 64 GQA), automatic 2-wait-state padding before PV MFMAs
# baseline (speedup 1.0000x reference)
.Lmla_B_ls_end:
	s_add_i32 s6, s14, -4
	s_and_b32 s6, s6, 2
	s_mul_i32 s7, s6, 0x2400
	v_add_f32_e32 v201, v91, v201
	v_add_f32_e32 v247, v92, v247
	v_add_f32_e32 v201, v93, v201
	v_add_f32_e32 v247, v94, v247
	v_add_f32_e32 v201, v95, v201
	v_add_f32_e32 v247, v96, v247
	s_waitcnt lgkmcnt(6)
	v_mfma_f32_32x32x16_bf16 v[50:65], v[238:241], v[126:129], v[50:65]
	ds_read_b128 v[238:241], v0 offset:6784
	v_add_f32_e32 v201, v97, v201
	v_add_f32_e32 v247, v98, v247
	v_add_f32_e32 v201, v99, v201
	v_add_f32_e32 v247, v100, v247
	v_add_f32_e32 v201, v101, v201
	v_add_f32_e32 v247, v102, v247
	s_waitcnt lgkmcnt(6)
	v_mfma_f32_32x32x16_bf16 v[50:65], v[242:245], v[130:133], v[50:65]
	ds_read_b128 v[242:245], v0 offset:6816
	v_add_f32_e32 v201, v103, v201
	v_add_f32_e32 v247, v104, v247
	v_add_f32_e32 v201, v105, v201
	v_add_f32_e32 v247, v106, v247
	v_add_f32_e32 v201, v107, v201
	v_add_f32_e32 v247, v108, v247
	s_waitcnt lgkmcnt(6)
	v_mfma_f32_32x32x16_bf16 v[50:65], v[162:165], v[134:137], v[50:65]
	ds_read_b128 v[162:165], v225
	v_add_f32_e32 v201, v109, v201
	v_add_f32_e32 v247, v110, v247
	v_add_f32_e32 v201, v111, v201
	v_add_f32_e32 v247, v112, v247
	v_add_f32_e32 v201, v113, v201
	v_add_f32_e32 v247, v246, v247
	s_waitcnt lgkmcnt(6)
	v_mfma_f32_32x32x16_bf16 v[66:81], v[166:169], v[114:117], v[34:49]
	ds_read_b128 v[166:169], v225 offset:32
	v_add_f32_e32 v201, v202, v201
	v_add_f32_e32 v247, v203, v247
	v_add_f32_e32 v201, v204, v201
	v_add_f32_e32 v247, v205, v247
	s_waitcnt lgkmcnt(6)
	v_mfma_f32_32x32x16_bf16 v[66:81], v[226:229], v[118:121], v[66:81]
	ds_read_b128 v[226:229], v225 offset:64
	v_add_f32_e32 v201, v206, v201
	v_add_f32_e32 v247, v207, v247
	v_add_f32_e32 v201, v208, v201
	v_add_f32_e32 v247, v209, v247
	s_waitcnt lgkmcnt(6)
	v_mfma_f32_32x32x16_bf16 v[66:81], v[230:233], v[122:125], v[66:81]
	ds_read_b128 v[230:233], v225 offset:96
	v_add_f32_e32 v201, v210, v201
	v_add_f32_e32 v247, v211, v247
	v_add_f32_e32 v201, v212, v201
	v_add_f32_e32 v247, v213, v247
	v_max3_f32 v0, v50, v51, v52
	v_max3_f32 v0, v0, v53, v54
	s_waitcnt lgkmcnt(6)
	v_mfma_f32_32x32x16_bf16 v[66:81], v[234:237], v[126:129], v[66:81]
	ds_read_b128 v[234:237], v225 offset:128
	v_add_f32_e32 v201, v214, v201
	v_add_f32_e32 v247, v215, v247
	v_add_f32_e32 v201, v216, v201
	v_add_f32_e32 v247, v217, v247
	v_max3_f32 v0, v0, v55, v56
	v_max3_f32 v0, v0, v57, v58
	s_waitcnt lgkmcnt(6)
	v_mfma_f32_32x32x16_bf16 v[66:81], v[238:241], v[130:133], v[66:81]
	ds_read_b128 v[238:241], v225 offset:160
	v_add_f32_e32 v201, v218, v201
	v_add_f32_e32 v247, v219, v247
	v_add_f32_e32 v201, v220, v201
	v_add_f32_e32 v247, v221, v247
	v_max3_f32 v0, v0, v59, v60
	v_max3_f32 v0, v0, v61, v62
	s_waitcnt lgkmcnt(6)
	v_mfma_f32_32x32x16_bf16 v[66:81], v[242:245], v[134:137], v[66:81]
	ds_read_b128 v[242:245], v225 offset:6656
	v_add_f32_e32 v201, v222, v201
	v_add_f32_e32 v247, v223, v247
	v_add_f32_e32 v201, v224, v201
	v_add_f32_e32 v201, v247, v201
	v_max3_f32 v0, v0, v63, v64
	v_max3_f32 v0, v0, v65, v65
	s_waitcnt lgkmcnt(6)
	v_mfma_f32_32x32x16_bf16 v[82:97], v[162:165], v[114:117], v[34:49]
	ds_read_b128 v[162:165], v225 offset:6688
	v_exp_f32_e32 v246, v50
	v_exp_f32_e32 v202, v51
	v_exp_f32_e32 v203, v52
	s_waitcnt lgkmcnt(6)
	v_mfma_f32_32x32x16_bf16 v[82:97], v[166:169], v[118:121], v[82:97]
	ds_read_b128 v[166:169], v225 offset:6720
	v_add3_u32 v247, v198, s7, v200
	v_exp_f32_e32 v204, v53
	v_exp_f32_e32 v205, v54
	v_exp_f32_e32 v206, v55
	s_waitcnt lgkmcnt(6)
	v_mfma_f32_32x32x16_bf16 v[82:97], v[226:229], v[122:125], v[82:97]
	ds_read_b128 v[226:229], v225 offset:6752
	v_max3_f32 v0, v0, v66, v67
	v_max3_f32 v0, v0, v68, v69
	v_exp_f32_e32 v207, v56
	v_exp_f32_e32 v208, v57
	s_waitcnt lgkmcnt(6)
	v_mfma_f32_32x32x16_bf16 v[82:97], v[230:233], v[126:129], v[82:97]
	ds_read_b128 v[230:233], v225 offset:6784
	v_max3_f32 v0, v0, v70, v71
	v_max3_f32 v0, v0, v72, v73
	v_exp_f32_e32 v209, v58
	v_exp_f32_e32 v210, v59
	s_waitcnt lgkmcnt(6)
	v_mfma_f32_32x32x16_bf16 v[82:97], v[234:237], v[130:133], v[82:97]
	ds_read_b128 v[234:237], v225 offset:6816
	v_max3_f32 v0, v0, v74, v75
	v_max3_f32 v0, v0, v76, v77
	v_exp_f32_e32 v211, v60
	v_exp_f32_e32 v212, v61
	s_waitcnt lgkmcnt(6)
	v_mfma_f32_32x32x16_bf16 v[82:97], v[238:241], v[134:137], v[82:97]
	ds_read_b128 v[238:241], v247 offset:53248
	v_max3_f32 v0, v0, v78, v79
	v_max3_f32 v0, v0, v80, v81
	v_exp_f32_e32 v213, v62
	v_exp_f32_e32 v214, v63
	s_waitcnt lgkmcnt(6)
	v_mfma_f32_32x32x16_bf16 v[98:113], v[242:245], v[114:117], v[34:49]
	ds_read_b128 v[242:245], v247 offset:57856
	v_exp_f32_e32 v215, v64
	v_exp_f32_e32 v216, v65
	s_waitcnt lgkmcnt(6)
	v_mfma_f32_32x32x16_bf16 v[98:113], v[162:165], v[118:121], v[98:113]
	v_exp_f32_e32 v217, v66
	v_exp_f32_e32 v218, v67
	v_exp_f32_e32 v219, v68
	s_waitcnt lgkmcnt(5)
	v_mfma_f32_32x32x16_bf16 v[98:113], v[166:169], v[122:125], v[98:113]
	v_exp_f32_e32 v220, v69
	v_exp_f32_e32 v221, v70
	v_exp_f32_e32 v222, v71
	s_waitcnt lgkmcnt(4)
	v_mfma_f32_32x32x16_bf16 v[98:113], v[226:229], v[126:129], v[98:113]
	ds_read_b128 v[226:229], v247 offset:53280
	v_exp_f32_e32 v223, v72
	v_exp_f32_e32 v224, v73
	s_waitcnt lgkmcnt(4)
	v_mfma_f32_32x32x16_bf16 v[98:113], v[230:233], v[130:133], v[98:113]
	ds_read_b128 v[230:233], v247 offset:57888
	s_waitcnt lgkmcnt(4)
	v_mfma_f32_32x32x16_bf16 v[98:113], v[234:237], v[134:137], v[98:113]
	ds_read_b128 v[234:237], v247 offset:53312
	v_max3_f32 v0, v0, v82, v83
	v_max3_f32 v0, v0, v84, v85
	v_max3_f32 v0, v0, v86, v87
	v_max3_f32 v0, v0, v88, v89
	v_max3_f32 v0, v0, v90, v91
	v_max3_f32 v0, v0, v92, v93
	v_max3_f32 v0, v0, v94, v95
	v_max3_f32 v0, v0, v96, v97
	s_nop 4
	v_max3_f32 v0, v0, v98, v99
	v_max3_f32 v0, v0, v100, v101
	v_max3_f32 v0, v0, v102, v103
	v_max3_f32 v0, v0, v104, v105
	v_max3_f32 v0, v0, v106, v107
	v_max3_f32 v0, v0, v108, v109
	v_max3_f32 v0, v0, v110, v111
	v_max3_f32 v0, v0, v112, v113
	v_mov_b32_e32 v162, v0
	s_nop 1
	v_permlane32_swap_b32_e32 v0, v162
	v_max_f32_e32 v0, v0, v162
	v_cmp_lt_f32_e32 vcc, s50, v0
	s_cbranch_vccz .LBB0_302
	v_max_f32_e32 v0, v0, v0
	v_max_f32_e32 v0, 0, v0
	v_exp_f32_e64 v162, -v0
	v_pk_add_f32 v[50:51], v[50:51], v[0:1] op_sel_hi:[1,0] neg_lo:[0,1] neg_hi:[0,1]
	v_pk_add_f32 v[66:67], v[66:67], v[0:1] op_sel_hi:[1,0] neg_lo:[0,1] neg_hi:[0,1]
	v_pk_add_f32 v[82:83], v[82:83], v[0:1] op_sel_hi:[1,0] neg_lo:[0,1] neg_hi:[0,1]
	v_mul_f32_e32 v201, v201, v162
	v_pk_mul_f32 v[16:17], v[16:17], v[162:163] op_sel_hi:[1,0]
	v_pk_mul_f32 v[14:15], v[14:15], v[162:163] op_sel_hi:[1,0]
	v_pk_mul_f32 v[12:13], v[12:13], v[162:163] op_sel_hi:[1,0]
	v_pk_mul_f32 v[10:11], v[10:11], v[162:163] op_sel_hi:[1,0]
	v_pk_mul_f32 v[8:9], v[8:9], v[162:163] op_sel_hi:[1,0]
	v_pk_mul_f32 v[6:7], v[6:7], v[162:163] op_sel_hi:[1,0]
	v_pk_mul_f32 v[4:5], v[4:5], v[162:163] op_sel_hi:[1,0]
	v_pk_mul_f32 v[2:3], v[2:3], v[162:163] op_sel_hi:[1,0]
	v_pk_mul_f32 v[32:33], v[32:33], v[162:163] op_sel_hi:[1,0]
	v_pk_mul_f32 v[30:31], v[30:31], v[162:163] op_sel_hi:[1,0]
	v_pk_mul_f32 v[28:29], v[28:29], v[162:163] op_sel_hi:[1,0]
	v_pk_mul_f32 v[26:27], v[26:27], v[162:163] op_sel_hi:[1,0]
	v_pk_mul_f32 v[24:25], v[24:25], v[162:163] op_sel_hi:[1,0]
	v_pk_mul_f32 v[22:23], v[22:23], v[162:163] op_sel_hi:[1,0]
	v_pk_mul_f32 v[20:21], v[20:21], v[162:163] op_sel_hi:[1,0]
	v_pk_mul_f32 v[18:19], v[18:19], v[162:163] op_sel_hi:[1,0]
	v_pk_add_f32 v[98:99], v[98:99], v[0:1] op_sel_hi:[1,0] neg_lo:[0,1] neg_hi:[0,1]
	v_pk_add_f32 v[52:53], v[52:53], v[0:1] op_sel_hi:[1,0] neg_lo:[0,1] neg_hi:[0,1]
	v_pk_add_f32 v[68:69], v[68:69], v[0:1] op_sel_hi:[1,0] neg_lo:[0,1] neg_hi:[0,1]
	v_pk_add_f32 v[84:85], v[84:85], v[0:1] op_sel_hi:[1,0] neg_lo:[0,1] neg_hi:[0,1]
	v_pk_add_f32 v[100:101], v[100:101], v[0:1] op_sel_hi:[1,0] neg_lo:[0,1] neg_hi:[0,1]
	v_pk_add_f32 v[54:55], v[54:55], v[0:1] op_sel_hi:[1,0] neg_lo:[0,1] neg_hi:[0,1]
	v_pk_add_f32 v[70:71], v[70:71], v[0:1] op_sel_hi:[1,0] neg_lo:[0,1] neg_hi:[0,1]
	v_pk_add_f32 v[86:87], v[86:87], v[0:1] op_sel_hi:[1,0] neg_lo:[0,1] neg_hi:[0,1]
	v_pk_add_f32 v[102:103], v[102:103], v[0:1] op_sel_hi:[1,0] neg_lo:[0,1] neg_hi:[0,1]
	v_pk_add_f32 v[56:57], v[56:57], v[0:1] op_sel_hi:[1,0] neg_lo:[0,1] neg_hi:[0,1]
	v_pk_add_f32 v[72:73], v[72:73], v[0:1] op_sel_hi:[1,0] neg_lo:[0,1] neg_hi:[0,1]
	v_pk_add_f32 v[88:89], v[88:89], v[0:1] op_sel_hi:[1,0] neg_lo:[0,1] neg_hi:[0,1]
	v_pk_add_f32 v[104:105], v[104:105], v[0:1] op_sel_hi:[1,0] neg_lo:[0,1] neg_hi:[0,1]
	v_pk_add_f32 v[58:59], v[58:59], v[0:1] op_sel_hi:[1,0] neg_lo:[0,1] neg_hi:[0,1]
	v_pk_add_f32 v[74:75], v[74:75], v[0:1] op_sel_hi:[1,0] neg_lo:[0,1] neg_hi:[0,1]
	v_pk_add_f32 v[90:91], v[90:91], v[0:1] op_sel_hi:[1,0] neg_lo:[0,1] neg_hi:[0,1]
	v_pk_add_f32 v[106:107], v[106:107], v[0:1] op_sel_hi:[1,0] neg_lo:[0,1] neg_hi:[0,1]
	v_pk_add_f32 v[60:61], v[60:61], v[0:1] op_sel_hi:[1,0] neg_lo:[0,1] neg_hi:[0,1]
	v_pk_add_f32 v[76:77], v[76:77], v[0:1] op_sel_hi:[1,0] neg_lo:[0,1] neg_hi:[0,1]
	v_pk_add_f32 v[92:93], v[92:93], v[0:1] op_sel_hi:[1,0] neg_lo:[0,1] neg_hi:[0,1]
	v_pk_add_f32 v[108:109], v[108:109], v[0:1] op_sel_hi:[1,0] neg_lo:[0,1] neg_hi:[0,1]
	v_pk_add_f32 v[62:63], v[62:63], v[0:1] op_sel_hi:[1,0] neg_lo:[0,1] neg_hi:[0,1]
	v_pk_add_f32 v[78:79], v[78:79], v[0:1] op_sel_hi:[1,0] neg_lo:[0,1] neg_hi:[0,1]
	v_pk_add_f32 v[94:95], v[94:95], v[0:1] op_sel_hi:[1,0] neg_lo:[0,1] neg_hi:[0,1]
	v_pk_add_f32 v[110:111], v[110:111], v[0:1] op_sel_hi:[1,0] neg_lo:[0,1] neg_hi:[0,1]
	v_pk_add_f32 v[64:65], v[64:65], v[0:1] op_sel_hi:[1,0] neg_lo:[0,1] neg_hi:[0,1]
	v_pk_add_f32 v[80:81], v[80:81], v[0:1] op_sel_hi:[1,0] neg_lo:[0,1] neg_hi:[0,1]
	v_pk_add_f32 v[96:97], v[96:97], v[0:1] op_sel_hi:[1,0] neg_lo:[0,1] neg_hi:[0,1]
	v_pk_add_f32 v[112:113], v[112:113], v[0:1] op_sel_hi:[1,0] neg_lo:[0,1] neg_hi:[0,1]
	v_sub_f32_e32 v49, v49, v0
	v_sub_f32_e32 v48, v48, v0
	v_sub_f32_e32 v47, v47, v0
	v_sub_f32_e32 v46, v46, v0
	v_sub_f32_e32 v45, v45, v0
	v_sub_f32_e32 v44, v44, v0
	v_sub_f32_e32 v43, v43, v0
	v_sub_f32_e32 v42, v42, v0
	v_sub_f32_e32 v41, v41, v0
	v_sub_f32_e32 v40, v40, v0
	v_sub_f32_e32 v39, v39, v0
	v_sub_f32_e32 v38, v38, v0
	v_sub_f32_e32 v37, v37, v0
	v_sub_f32_e32 v36, v36, v0
	v_sub_f32_e32 v35, v35, v0
	v_sub_f32_e32 v34, v34, v0
	v_mul_f32_e32 v246, v246, v162
	v_mul_f32_e32 v202, v202, v162
	v_mul_f32_e32 v203, v203, v162
	v_mul_f32_e32 v204, v204, v162
	v_mul_f32_e32 v205, v205, v162
	v_mul_f32_e32 v206, v206, v162
	v_mul_f32_e32 v207, v207, v162
	v_mul_f32_e32 v208, v208, v162
	v_mul_f32_e32 v209, v209, v162
	v_mul_f32_e32 v210, v210, v162
	v_mul_f32_e32 v211, v211, v162
	v_mul_f32_e32 v212, v212, v162
	v_mul_f32_e32 v213, v213, v162
	v_mul_f32_e32 v214, v214, v162
	v_mul_f32_e32 v215, v215, v162
	v_mul_f32_e32 v216, v216, v162
	v_mul_f32_e32 v217, v217, v162
	v_mul_f32_e32 v218, v218, v162
	v_mul_f32_e32 v219, v219, v162
	v_mul_f32_e32 v220, v220, v162
	v_mul_f32_e32 v221, v221, v162
	v_mul_f32_e32 v222, v222, v162
	v_mul_f32_e32 v223, v223, v162
	v_mul_f32_e32 v224, v224, v162
.LBB0_302:
	s_addk_i32 s7, 0x2400
	v_add3_u32 v0, v198, s7, v200
	v_cvt_pk_bf16_f32 v166, v246, v202
	v_cvt_pk_bf16_f32 v167, v203, v204
	v_cvt_pk_bf16_f32 v168, v205, v206
	v_cvt_pk_bf16_f32 v169, v207, v208
	s_nop 0
	s_waitcnt lgkmcnt(4)
	v_mfma_f32_32x32x16_bf16 v[18:33], v[238:241], v[166:169], v[18:33]
	ds_read_b128 v[238:241], v247 offset:57920
	s_waitcnt lgkmcnt(4)
	v_mfma_f32_32x32x16_bf16 v[2:17], v[242:245], v[166:169], v[2:17]
	ds_read_b128 v[242:245], v247 offset:53344
	v_cvt_pk_bf16_f32 v162, v209, v210
	v_cvt_pk_bf16_f32 v163, v211, v212
	v_cvt_pk_bf16_f32 v164, v213, v214
	v_cvt_pk_bf16_f32 v165, v215, v216
	s_nop 0
	s_waitcnt lgkmcnt(4)
	v_mfma_f32_32x32x16_bf16 v[18:33], v[226:229], v[162:165], v[18:33]
	ds_read_b128 v[226:229], v247 offset:57952
	v_cvt_pk_bf16_f32 v70, v217, v218
	s_waitcnt lgkmcnt(4)
	v_mfma_f32_32x32x16_bf16 v[2:17], v[230:233], v[162:165], v[2:17]
	ds_read_b128 v[230:233], v0 offset:53248
	v_cvt_pk_bf16_f32 v71, v219, v220
	v_cvt_pk_bf16_f32 v72, v221, v222
	v_cvt_pk_bf16_f32 v73, v223, v224
	v_exp_f32_e32 v74, v74
	v_exp_f32_e32 v75, v75
	v_exp_f32_e32 v76, v76
	s_waitcnt lgkmcnt(4)
	v_mfma_f32_32x32x16_bf16 v[18:33], v[234:237], v[70:73], v[18:33]
	ds_read_b128 v[234:237], v0 offset:57856
	v_exp_f32_e32 v77, v77
	v_exp_f32_e32 v78, v78
	v_exp_f32_e32 v79, v79
	v_exp_f32_e32 v80, v80
	v_exp_f32_e32 v81, v81
	v_cvt_pk_bf16_f32 v66, v74, v75
	s_waitcnt lgkmcnt(4)
	v_mfma_f32_32x32x16_bf16 v[2:17], v[238:241], v[70:73], v[2:17]
	ds_read_b128 v[238:241], v0 offset:53280
	v_cvt_pk_bf16_f32 v67, v76, v77
	v_cvt_pk_bf16_f32 v68, v78, v79
	v_cvt_pk_bf16_f32 v69, v80, v81
	v_exp_f32_e32 v82, v82
	v_exp_f32_e32 v83, v83
	s_waitcnt lgkmcnt(4)
	v_mfma_f32_32x32x16_bf16 v[18:33], v[242:245], v[66:69], v[18:33]
	ds_read_b128 v[242:245], v0 offset:57888
	v_exp_f32_e32 v84, v84
	v_exp_f32_e32 v85, v85
	v_exp_f32_e32 v86, v86
	v_exp_f32_e32 v87, v87
	v_exp_f32_e32 v88, v88
	v_exp_f32_e32 v89, v89
	s_waitcnt lgkmcnt(4)
	v_mfma_f32_32x32x16_bf16 v[2:17], v[226:229], v[66:69], v[2:17]
	ds_read_b128 v[226:229], v0 offset:53312
	v_cvt_pk_bf16_f32 v62, v82, v83
	v_cvt_pk_bf16_f32 v63, v84, v85
	v_cvt_pk_bf16_f32 v64, v86, v87
	v_cvt_pk_bf16_f32 v65, v88, v89
	v_exp_f32_e32 v90, v90
	v_exp_f32_e32 v91, v91
	s_waitcnt lgkmcnt(4)
	v_mfma_f32_32x32x16_bf16 v[18:33], v[230:233], v[62:65], v[18:33]
	ds_read_b128 v[230:233], v0 offset:57920
	v_exp_f32_e32 v92, v92
	v_exp_f32_e32 v93, v93
	v_exp_f32_e32 v94, v94
	v_exp_f32_e32 v95, v95
	v_exp_f32_e32 v96, v96
	v_exp_f32_e32 v97, v97
	s_waitcnt lgkmcnt(4)
	v_mfma_f32_32x32x16_bf16 v[2:17], v[234:237], v[62:65], v[2:17]
	ds_read_b128 v[234:237], v0 offset:53344
	v_cvt_pk_bf16_f32 v58, v90, v91
	v_cvt_pk_bf16_f32 v59, v92, v93
	v_cvt_pk_bf16_f32 v60, v94, v95
	v_cvt_pk_bf16_f32 v61, v96, v97
	v_exp_f32_e32 v98, v98
	v_exp_f32_e32 v99, v99
	s_waitcnt lgkmcnt(4)
	v_mfma_f32_32x32x16_bf16 v[18:33], v[238:241], v[58:61], v[18:33]
	ds_read_b128 v[238:241], v0 offset:57952
	v_exp_f32_e32 v100, v100
	v_exp_f32_e32 v101, v101
	v_exp_f32_e32 v102, v102
	v_exp_f32_e32 v103, v103
	v_exp_f32_e32 v104, v104
	v_exp_f32_e32 v105, v105
	v_cvt_pk_bf16_f32 v54, v98, v99
	s_waitcnt lgkmcnt(4)
	v_mfma_f32_32x32x16_bf16 v[2:17], v[242:245], v[58:61], v[2:17]
	v_cvt_pk_bf16_f32 v55, v100, v101
	v_cvt_pk_bf16_f32 v56, v102, v103
	v_cvt_pk_bf16_f32 v57, v104, v105
	v_exp_f32_e32 v106, v106
	v_exp_f32_e32 v107, v107
	v_exp_f32_e32 v108, v108
	s_waitcnt lgkmcnt(3)
	v_mfma_f32_32x32x16_bf16 v[18:33], v[226:229], v[54:57], v[18:33]
	v_exp_f32_e32 v109, v109
	v_exp_f32_e32 v110, v110
	v_exp_f32_e32 v111, v111
	v_exp_f32_e32 v112, v112
	v_exp_f32_e32 v113, v113
	v_cvt_pk_bf16_f32 v50, v106, v107
	s_waitcnt lgkmcnt(2)
	v_mfma_f32_32x32x16_bf16 v[2:17], v[230:233], v[54:57], v[2:17]
	v_cvt_pk_bf16_f32 v51, v108, v109
	v_cvt_pk_bf16_f32 v52, v110, v111
	v_cvt_pk_bf16_f32 v53, v112, v113
	s_add_i32 s15, s14, -2
	s_cmp_ge_u32 s15, s23
	s_waitcnt lgkmcnt(1)
	v_mfma_f32_32x32x16_bf16 v[18:33], v[234:237], v[50:53], v[18:33]
	s_waitcnt lgkmcnt(0)
	v_mfma_f32_32x32x16_bf16 v[2:17], v[238:241], v[50:53], v[2:17]
	s_branch .LBB0_299

.Lgqa_B_ls_end:
	v_add_f32_e32 v165, v111, v165
	v_add_f32_e32 v242, v112, v242
	v_add_f32_e32 v165, v113, v165
	v_add_f32_e32 v242, v82, v242
	v_add_f32_e32 v165, v83, v165
	v_add_f32_e32 v242, v84, v242
	s_waitcnt lgkmcnt(6)
	v_mfma_f32_32x32x16_bf16 v[50:65], v[226:229], v[126:129], v[50:65]
	ds_read_b128 v[226:229], v0 offset:64
	v_add_f32_e32 v165, v85, v165
	v_add_f32_e32 v242, v86, v242
	v_add_f32_e32 v165, v87, v165
	v_add_f32_e32 v242, v88, v242
	v_add_f32_e32 v165, v89, v165
	v_add_f32_e32 v242, v90, v242
	s_waitcnt lgkmcnt(6)
	v_mfma_f32_32x32x16_bf16 v[66:81], v[230:233], v[114:117], v[34:49]
	ds_read_b128 v[230:233], v0 offset:96
	v_add_f32_e32 v165, v91, v165
	v_add_f32_e32 v242, v92, v242
	v_add_f32_e32 v165, v93, v165
	v_add_f32_e32 v242, v94, v242
	v_add_f32_e32 v165, v95, v165
	s_waitcnt lgkmcnt(6)
	v_mfma_f32_32x32x16_bf16 v[66:81], v[234:237], v[118:121], v[66:81]
	ds_read_b128 v[234:237], v0 offset:13824
	v_add_f32_e32 v242, v96, v242
	v_add_f32_e32 v165, v97, v165
	v_add_f32_e32 v242, v166, v242
	v_add_f32_e32 v165, v167, v165
	v_add_f32_e32 v242, v168, v242
	s_waitcnt lgkmcnt(6)
	v_mfma_f32_32x32x16_bf16 v[66:81], v[238:241], v[122:125], v[66:81]
	ds_read_b128 v[238:241], v0 offset:13856
	v_add_f32_e32 v165, v169, v165
	v_add_f32_e32 v242, v170, v242
	v_add_f32_e32 v165, v171, v165
	v_add_f32_e32 v242, v172, v242
	v_add_f32_e32 v165, v173, v165
	v_max3_f32 v146, v50, v51, v52
	v_max3_f32 v146, v146, v53, v54
	s_waitcnt lgkmcnt(6)
	v_mfma_f32_32x32x16_bf16 v[66:81], v[214:217], v[126:129], v[66:81]
	ds_read_b128 v[214:217], v0 offset:13888
	v_add_f32_e32 v242, v174, v242
	v_add_f32_e32 v165, v175, v165
	v_add_f32_e32 v242, v176, v242
	v_add_f32_e32 v165, v177, v165
	v_add_f32_e32 v242, v178, v242
	v_max3_f32 v146, v146, v55, v56
	v_max3_f32 v146, v146, v57, v58
	s_waitcnt lgkmcnt(6)
	v_mfma_f32_32x32x16_bf16 v[98:113], v[218:221], v[114:117], v[34:49]
	ds_read_b128 v[218:221], v0 offset:13920
	v_add_f32_e32 v165, v179, v165
	v_add_f32_e32 v242, v191, v242
	v_add_f32_e32 v165, v192, v165
	v_add_f32_e32 v242, v193, v242
	v_max3_f32 v146, v146, v59, v60
	v_max3_f32 v146, v146, v61, v62
	s_waitcnt lgkmcnt(6)
	v_mfma_f32_32x32x16_bf16 v[98:113], v[222:225], v[118:121], v[98:113]
	ds_read_b128 v[206:209], v0 offset:36864
	v_add_f32_e32 v165, v194, v165
	v_add_f32_e32 v242, v195, v242
	v_add_f32_e32 v165, v196, v165
	v_add_f32_e32 v242, v197, v242
	v_max3_f32 v146, v146, v63, v64
	v_max3_f32 v146, v146, v65, v65
	s_waitcnt lgkmcnt(6)
	v_mfma_f32_32x32x16_bf16 v[98:113], v[226:229], v[122:125], v[98:113]
	ds_read_b128 v[210:213], v0 offset:41472
	v_add_f32_e32 v165, v198, v165
	v_add_f32_e32 v242, v199, v242
	v_add_f32_e32 v165, v200, v165
	v_add_f32_e32 v242, v201, v242
	v_max3_f32 v146, v146, v66, v67
	v_max3_f32 v146, v146, v68, v69
	s_waitcnt lgkmcnt(6)
	v_mfma_f32_32x32x16_bf16 v[98:113], v[230:233], v[126:129], v[98:113]
	ds_read_b128 v[222:225], v0 offset:36896
	v_add_f32_e32 v165, v202, v165
	v_add_f32_e32 v242, v203, v242
	v_add_f32_e32 v165, v204, v165
	v_add_f32_e32 v165, v242, v165
	v_max3_f32 v146, v146, v70, v71
	v_max3_f32 v146, v146, v72, v73
	s_waitcnt lgkmcnt(6)
	v_mfma_f32_32x32x16_bf16 v[82:97], v[234:237], v[114:117], v[34:49]
	ds_read_b128 v[226:229], v0 offset:41504
	v_max3_f32 v146, v146, v74, v75
	v_max3_f32 v146, v146, v76, v77
	v_exp_f32_e32 v196, v53
	v_exp_f32_e32 v197, v54
	v_exp_f32_e32 v198, v55
	s_waitcnt lgkmcnt(6)
	v_mfma_f32_32x32x16_bf16 v[82:97], v[238:241], v[118:121], v[82:97]
	ds_read_b128 v[230:233], v0 offset:36928
	v_max3_f32 v146, v146, v78, v79
	v_max3_f32 v146, v146, v80, v81
	v_exp_f32_e32 v199, v56
	v_exp_f32_e32 v200, v57
	v_exp_f32_e32 v204, v61
	s_waitcnt lgkmcnt(6)
	v_mfma_f32_32x32x16_bf16 v[82:97], v[214:217], v[122:125], v[82:97]
	ds_read_b128 v[234:237], v0 offset:41536
	v_exp_f32_e32 v193, v50
	v_exp_f32_e32 v194, v51
	v_exp_f32_e32 v195, v52
	s_waitcnt lgkmcnt(6)
	v_mfma_f32_32x32x16_bf16 v[82:97], v[218:221], v[126:129], v[82:97]
	v_exp_f32_e32 v201, v58
	v_exp_f32_e32 v202, v59
	v_exp_f32_e32 v203, v60
	v_max3_f32 v146, v146, v98, v99
	v_max3_f32 v146, v146, v100, v101
	v_max3_f32 v146, v146, v102, v103
	v_max3_f32 v146, v146, v104, v105
	v_max3_f32 v146, v146, v106, v107
	v_max3_f32 v146, v146, v108, v109
	v_max3_f32 v146, v146, v110, v111
	v_max3_f32 v146, v146, v112, v113
	s_nop 3
	v_max3_f32 v146, v146, v82, v83
	v_max3_f32 v146, v146, v84, v85
	v_max3_f32 v146, v146, v86, v87
	v_max3_f32 v146, v146, v88, v89
	v_max3_f32 v146, v146, v90, v91
	v_max3_f32 v146, v146, v92, v93
	v_max3_f32 v146, v146, v94, v95
	v_max3_f32 v146, v146, v96, v97
	v_mov_b32_e32 v147, v146
	s_nop 1
	v_permlane32_swap_b32_e32 v146, v147
	v_max_f32_e32 v146, v146, v147
	v_cmp_lt_f32_e32 vcc, s50, v146
	s_cbranch_vccz .LBB0_350
	v_max_f32_e32 v146, v146, v146
	v_max_f32_e32 v146, 0, v146
	v_exp_f32_e64 v148, -v146
	v_pk_add_f32 v[98:99], v[98:99], v[146:147] op_sel_hi:[1,0] neg_lo:[0,1] neg_hi:[0,1]
	v_pk_add_f32 v[66:67], v[66:67], v[146:147] op_sel_hi:[1,0] neg_lo:[0,1] neg_hi:[0,1]
	v_pk_add_f32 v[50:51], v[50:51], v[146:147] op_sel_hi:[1,0] neg_lo:[0,1] neg_hi:[0,1]
	v_mul_f32_e32 v165, v165, v148
	v_pk_mul_f32 v[16:17], v[16:17], v[148:149] op_sel_hi:[1,0]
	v_pk_mul_f32 v[14:15], v[14:15], v[148:149] op_sel_hi:[1,0]
	v_pk_mul_f32 v[12:13], v[12:13], v[148:149] op_sel_hi:[1,0]
	v_pk_mul_f32 v[10:11], v[10:11], v[148:149] op_sel_hi:[1,0]
	v_pk_mul_f32 v[8:9], v[8:9], v[148:149] op_sel_hi:[1,0]
	v_pk_mul_f32 v[6:7], v[6:7], v[148:149] op_sel_hi:[1,0]
	v_pk_mul_f32 v[4:5], v[4:5], v[148:149] op_sel_hi:[1,0]
	v_pk_mul_f32 v[2:3], v[2:3], v[148:149] op_sel_hi:[1,0]
	v_pk_mul_f32 v[32:33], v[32:33], v[148:149] op_sel_hi:[1,0]
	v_pk_mul_f32 v[30:31], v[30:31], v[148:149] op_sel_hi:[1,0]
	v_pk_mul_f32 v[28:29], v[28:29], v[148:149] op_sel_hi:[1,0]
	v_pk_mul_f32 v[26:27], v[26:27], v[148:149] op_sel_hi:[1,0]
	v_pk_mul_f32 v[24:25], v[24:25], v[148:149] op_sel_hi:[1,0]
	v_pk_mul_f32 v[22:23], v[22:23], v[148:149] op_sel_hi:[1,0]
	v_pk_mul_f32 v[20:21], v[20:21], v[148:149] op_sel_hi:[1,0]
	v_pk_mul_f32 v[18:19], v[18:19], v[148:149] op_sel_hi:[1,0]
	v_pk_add_f32 v[82:83], v[82:83], v[146:147] op_sel_hi:[1,0] neg_lo:[0,1] neg_hi:[0,1]
	v_pk_add_f32 v[100:101], v[100:101], v[146:147] op_sel_hi:[1,0] neg_lo:[0,1] neg_hi:[0,1]
	v_pk_add_f32 v[68:69], v[68:69], v[146:147] op_sel_hi:[1,0] neg_lo:[0,1] neg_hi:[0,1]
	v_pk_add_f32 v[52:53], v[52:53], v[146:147] op_sel_hi:[1,0] neg_lo:[0,1] neg_hi:[0,1]
	v_pk_add_f32 v[84:85], v[84:85], v[146:147] op_sel_hi:[1,0] neg_lo:[0,1] neg_hi:[0,1]
	v_pk_add_f32 v[102:103], v[102:103], v[146:147] op_sel_hi:[1,0] neg_lo:[0,1] neg_hi:[0,1]
	v_pk_add_f32 v[70:71], v[70:71], v[146:147] op_sel_hi:[1,0] neg_lo:[0,1] neg_hi:[0,1]
	v_pk_add_f32 v[54:55], v[54:55], v[146:147] op_sel_hi:[1,0] neg_lo:[0,1] neg_hi:[0,1]
	v_pk_add_f32 v[86:87], v[86:87], v[146:147] op_sel_hi:[1,0] neg_lo:[0,1] neg_hi:[0,1]
	v_pk_add_f32 v[104:105], v[104:105], v[146:147] op_sel_hi:[1,0] neg_lo:[0,1] neg_hi:[0,1]
	v_pk_add_f32 v[72:73], v[72:73], v[146:147] op_sel_hi:[1,0] neg_lo:[0,1] neg_hi:[0,1]
	v_pk_add_f32 v[56:57], v[56:57], v[146:147] op_sel_hi:[1,0] neg_lo:[0,1] neg_hi:[0,1]
	v_pk_add_f32 v[88:89], v[88:89], v[146:147] op_sel_hi:[1,0] neg_lo:[0,1] neg_hi:[0,1]
	v_pk_add_f32 v[106:107], v[106:107], v[146:147] op_sel_hi:[1,0] neg_lo:[0,1] neg_hi:[0,1]
	v_pk_add_f32 v[74:75], v[74:75], v[146:147] op_sel_hi:[1,0] neg_lo:[0,1] neg_hi:[0,1]
	v_pk_add_f32 v[58:59], v[58:59], v[146:147] op_sel_hi:[1,0] neg_lo:[0,1] neg_hi:[0,1]
	v_pk_add_f32 v[90:91], v[90:91], v[146:147] op_sel_hi:[1,0] neg_lo:[0,1] neg_hi:[0,1]
	v_pk_add_f32 v[108:109], v[108:109], v[146:147] op_sel_hi:[1,0] neg_lo:[0,1] neg_hi:[0,1]
	v_pk_add_f32 v[76:77], v[76:77], v[146:147] op_sel_hi:[1,0] neg_lo:[0,1] neg_hi:[0,1]
	v_pk_add_f32 v[60:61], v[60:61], v[146:147] op_sel_hi:[1,0] neg_lo:[0,1] neg_hi:[0,1]
	v_pk_add_f32 v[92:93], v[92:93], v[146:147] op_sel_hi:[1,0] neg_lo:[0,1] neg_hi:[0,1]
	v_pk_add_f32 v[110:111], v[110:111], v[146:147] op_sel_hi:[1,0] neg_lo:[0,1] neg_hi:[0,1]
	v_pk_add_f32 v[78:79], v[78:79], v[146:147] op_sel_hi:[1,0] neg_lo:[0,1] neg_hi:[0,1]
	v_pk_add_f32 v[62:63], v[62:63], v[146:147] op_sel_hi:[1,0] neg_lo:[0,1] neg_hi:[0,1]
	v_pk_add_f32 v[94:95], v[94:95], v[146:147] op_sel_hi:[1,0] neg_lo:[0,1] neg_hi:[0,1]
	v_pk_add_f32 v[112:113], v[112:113], v[146:147] op_sel_hi:[1,0] neg_lo:[0,1] neg_hi:[0,1]
	v_pk_add_f32 v[80:81], v[80:81], v[146:147] op_sel_hi:[1,0] neg_lo:[0,1] neg_hi:[0,1]
	v_pk_add_f32 v[64:65], v[64:65], v[146:147] op_sel_hi:[1,0] neg_lo:[0,1] neg_hi:[0,1]
	v_pk_add_f32 v[96:97], v[96:97], v[146:147] op_sel_hi:[1,0] neg_lo:[0,1] neg_hi:[0,1]
	v_sub_f32_e32 v49, v49, v146
	v_sub_f32_e32 v48, v48, v146
	v_sub_f32_e32 v47, v47, v146
	v_sub_f32_e32 v46, v46, v146
	v_sub_f32_e32 v45, v45, v146
	v_sub_f32_e32 v44, v44, v146
	v_sub_f32_e32 v43, v43, v146
	v_sub_f32_e32 v42, v42, v146
	v_sub_f32_e32 v41, v41, v146
	v_sub_f32_e32 v40, v40, v146
	v_sub_f32_e32 v39, v39, v146
	v_sub_f32_e32 v38, v38, v146
	v_sub_f32_e32 v37, v37, v146
	v_sub_f32_e32 v36, v36, v146
	v_sub_f32_e32 v35, v35, v146
	v_sub_f32_e32 v34, v34, v146
	v_mul_f32_e32 v196, v196, v148
	v_mul_f32_e32 v197, v197, v148
	v_mul_f32_e32 v198, v198, v148
	v_mul_f32_e32 v199, v199, v148
	v_mul_f32_e32 v200, v200, v148
	v_mul_f32_e32 v204, v204, v148
	v_mul_f32_e32 v193, v193, v148
	v_mul_f32_e32 v194, v194, v148
	v_mul_f32_e32 v195, v195, v148
	v_mul_f32_e32 v201, v201, v148
	v_mul_f32_e32 v202, v202, v148
	v_mul_f32_e32 v203, v203, v148
.LBB0_350:
	v_exp_f32_e32 v166, v98
	v_exp_f32_e32 v167, v99
	v_exp_f32_e32 v168, v100
	v_exp_f32_e32 v169, v101
	v_exp_f32_e32 v170, v102
	v_exp_f32_e32 v171, v103
	v_exp_f32_e32 v172, v104
	v_exp_f32_e32 v173, v105
	v_cvt_pk_bf16_f32 v146, v166, v167
	v_cvt_pk_bf16_f32 v147, v168, v169
	v_cvt_pk_bf16_f32 v148, v170, v171
	v_cvt_pk_bf16_f32 v149, v172, v173
	v_exp_f32_e32 v106, v106
	v_exp_f32_e32 v107, v107
	s_waitcnt lgkmcnt(5)
	v_mfma_f32_32x32x16_bf16 v[18:33], v[206:209], v[146:149], v[18:33]
	ds_read_b128 v[206:209], v0 offset:36960
	v_exp_f32_e32 v108, v108
	v_exp_f32_e32 v109, v109
	v_exp_f32_e32 v110, v110
	v_exp_f32_e32 v111, v111
	v_exp_f32_e32 v112, v112
	v_exp_f32_e32 v113, v113
	s_waitcnt lgkmcnt(5)
	v_mfma_f32_32x32x16_bf16 v[2:17], v[210:213], v[146:149], v[2:17]
	ds_read_b128 v[210:213], v0 offset:41568
	v_cvt_pk_bf16_f32 v102, v106, v107
	v_cvt_pk_bf16_f32 v103, v108, v109
	v_cvt_pk_bf16_f32 v104, v110, v111
	v_cvt_pk_bf16_f32 v105, v112, v113
	v_exp_f32_e32 v174, v66
	v_exp_f32_e32 v175, v67
	s_waitcnt lgkmcnt(5)
	v_mfma_f32_32x32x16_bf16 v[18:33], v[222:225], v[102:105], v[18:33]
	ds_read_b128 v[222:225], v0 offset:46080
	v_exp_f32_e32 v176, v68
	v_exp_f32_e32 v177, v69
	v_exp_f32_e32 v178, v70
	v_exp_f32_e32 v179, v71
	v_exp_f32_e32 v191, v72
	v_exp_f32_e32 v192, v73
	v_cvt_pk_bf16_f32 v98, v174, v175
	s_waitcnt lgkmcnt(5)
	v_mfma_f32_32x32x16_bf16 v[2:17], v[226:229], v[102:105], v[2:17]
	ds_read_b128 v[226:229], v0 offset:50688
	v_cvt_pk_bf16_f32 v99, v176, v177
	v_cvt_pk_bf16_f32 v100, v178, v179
	v_cvt_pk_bf16_f32 v101, v191, v192
	v_exp_f32_e32 v74, v74
	v_exp_f32_e32 v75, v75
	v_exp_f32_e32 v76, v76
	s_waitcnt lgkmcnt(5)
	v_mfma_f32_32x32x16_bf16 v[18:33], v[230:233], v[98:101], v[18:33]
	ds_read_b128 v[230:233], v0 offset:46112
	v_exp_f32_e32 v77, v77
	v_exp_f32_e32 v78, v78
	v_exp_f32_e32 v79, v79
	v_exp_f32_e32 v80, v80
	v_exp_f32_e32 v81, v81
	v_cvt_pk_bf16_f32 v70, v74, v75
	s_waitcnt lgkmcnt(5)
	v_mfma_f32_32x32x16_bf16 v[2:17], v[234:237], v[98:101], v[2:17]
	ds_read_b128 v[234:237], v0 offset:50720
	v_cvt_pk_bf16_f32 v71, v76, v77
	v_cvt_pk_bf16_f32 v72, v78, v79
	v_cvt_pk_bf16_f32 v73, v80, v81
	s_nop 0
	s_waitcnt lgkmcnt(5)
	v_mfma_f32_32x32x16_bf16 v[18:33], v[206:209], v[70:73], v[18:33]
	ds_read_b128 v[206:209], v0 offset:46144
	v_cvt_pk_bf16_f32 v66, v193, v194
	s_waitcnt lgkmcnt(5)
	v_mfma_f32_32x32x16_bf16 v[2:17], v[210:213], v[70:73], v[2:17]
	ds_read_b128 v[210:213], v0 offset:50752
	v_cvt_pk_bf16_f32 v67, v195, v196
	v_cvt_pk_bf16_f32 v68, v197, v198
	v_cvt_pk_bf16_f32 v69, v199, v200
	s_nop 0
	s_waitcnt lgkmcnt(5)
	v_mfma_f32_32x32x16_bf16 v[18:33], v[222:225], v[66:69], v[18:33]
	ds_read_b128 v[222:225], v0 offset:46176
	v_exp_f32_e32 v62, v62
	v_exp_f32_e32 v63, v63
	v_exp_f32_e32 v64, v64
	v_exp_f32_e32 v65, v65
	v_cvt_pk_bf16_f32 v58, v201, v202
	s_waitcnt lgkmcnt(5)
	v_mfma_f32_32x32x16_bf16 v[2:17], v[226:229], v[66:69], v[2:17]
	ds_read_b128 v[226:229], v0 offset:50784
	v_cvt_pk_bf16_f32 v59, v203, v204
	v_cvt_pk_bf16_f32 v60, v62, v63
	v_cvt_pk_bf16_f32 v61, v64, v65
	v_exp_f32_e32 v82, v82
	v_exp_f32_e32 v83, v83
	v_exp_f32_e32 v84, v84
	s_waitcnt lgkmcnt(5)
	v_mfma_f32_32x32x16_bf16 v[18:33], v[230:233], v[58:61], v[18:33]
	v_exp_f32_e32 v85, v85
	v_exp_f32_e32 v86, v86
	v_exp_f32_e32 v87, v87
	v_exp_f32_e32 v88, v88
	v_exp_f32_e32 v89, v89
	v_cvt_pk_bf16_f32 v54, v82, v83
	s_waitcnt lgkmcnt(4)
	v_mfma_f32_32x32x16_bf16 v[2:17], v[234:237], v[58:61], v[2:17]
	v_cvt_pk_bf16_f32 v55, v84, v85
	v_cvt_pk_bf16_f32 v56, v86, v87
	v_cvt_pk_bf16_f32 v57, v88, v89
	v_exp_f32_e32 v90, v90
	v_exp_f32_e32 v91, v91
	v_exp_f32_e32 v92, v92
	s_waitcnt lgkmcnt(3)
	v_mfma_f32_32x32x16_bf16 v[18:33], v[206:209], v[54:57], v[18:33]
	v_exp_f32_e32 v93, v93
	v_exp_f32_e32 v94, v94
	v_exp_f32_e32 v95, v95
	v_exp_f32_e32 v96, v96
	v_exp_f32_e32 v97, v97
	v_cvt_pk_bf16_f32 v50, v90, v91
	s_waitcnt lgkmcnt(2)
	v_mfma_f32_32x32x16_bf16 v[2:17], v[210:213], v[54:57], v[2:17]
	v_cvt_pk_bf16_f32 v51, v92, v93
	v_cvt_pk_bf16_f32 v52, v94, v95
	v_cvt_pk_bf16_f32 v53, v96, v97
	s_add_i32 s13, s12, -2
	s_cmp_ge_u32 s13, s23
	s_waitcnt lgkmcnt(1)
	v_mfma_f32_32x32x16_bf16 v[18:33], v[222:225], v[50:53], v[18:33]
	s_waitcnt lgkmcnt(0)
	v_mfma_f32_32x32x16_bf16 v[2:17], v[226:229], v[50:53], v[2:17]
	s_branch .LBB0_347
